# speedup vs baseline: 1.0258x; 1.0040x over previous
.LBB0_85:
	v_mov_b32_e32 v40, v240
	v_mov_b64_e32 v[0:1], s[64:65]
	v_readfirstlane_b32 s17, v40
	s_ashr_i32 s19, s17, 6
	s_and_b32 s18, s19, 3
	s_lshl_b32 s10, s18, 5
	v_and_b32_e32 v6, 31, v40
	s_add_i32 s10, s10, s5
	v_add_u32_e32 v194, s10, v6
	s_movk_i32 s5, 0x5800
	s_lshl_b32 s3, s3, 7
	s_ashr_i32 s20, s17, 8
	v_mad_i64_i32 v[196:197], s[10:11], v194, s5, v[0:1]
	s_and_b32 s3, s3, 0x380
	s_lshl_b32 s90, s3, 1
	s_lshl_b32 s10, s20, 6
	v_bfe_u32 v41, v40, 5, 1
	v_lshl_add_u64 v[2:3], v[196:197], 0, s[90:91]
	s_ashr_i32 s11, s10, 31
	v_lshl_add_u64 v[2:3], s[10:11], 1, v[2:3]
	v_lshlrev_b32_e32 v128, 4, v41
	v_lshl_add_u64 v[2:3], v[2:3], 0, v[128:129]
	global_load_dwordx4 v[130:133], v[2:3], off
	global_load_dwordx4 v[134:137], v[2:3], off offset:32
	global_load_dwordx4 v[138:141], v[2:3], off offset:64
	global_load_dwordx4 v[142:145], v[2:3], off offset:96
	v_bfe_u32 v2, v40, 3, 3
	v_lshl_or_b32 v2, s19, 3, v2
	v_mad_i64_i32 v[0:1], s[10:11], v2, s5, v[0:1]
	v_lshrrev_b32_e32 v3, 1, v2
	s_and_b32 s10, s19, 1
	v_bfe_u32 v2, v40, 2, 4
	v_lshlrev_b32_e32 v6, 7, v6
	v_lshl_or_b32 v2, s10, 5, v2
	v_lshl_or_b32 v43, s20, 13, v6
	v_lshrrev_b32_e32 v6, 1, v40
	v_xor_b32_e32 v7, v3, v40
	v_mul_u32_u24_e32 v2, 0x2c00, v2
	v_bitop3_b32 v6, v41, v6, 7 bitop3:0x78
	v_lshlrev_b32_e32 v128, 1, v2
	v_lshlrev_b32_e32 v4, 3, v40
	v_lshl_or_b32 v204, v6, 4, v43
	v_lshlrev_b32_e32 v6, 4, v7
	s_ashr_i32 s11, s17, 7
	v_lshl_add_u64 v[2:3], s[64:65], 0, v[128:129]
	v_and_b32_e32 v42, 24, v4
	v_lshl_add_u64 v[0:1], v[0:1], 0, s[90:91]
	v_and_b32_e32 v128, 0x70, v6
	v_lshl_or_b32 v4, s11, 5, v42
	s_lshl_b32 s5, s19, 10
	s_lshl_b32 s10, s10, 11
	s_lshl_b32 s11, s11, 12
	v_lshl_add_u64 v[198:199], v[0:1], 0, v[128:129]
	v_lshl_add_u64 v[0:1], v[198:199], 0, s[72:73]
	s_or_b32 s24, s10, s11
	s_add_i32 s19, s5, 0
	s_mov_b32 s10, m0
	s_mov_b32 m0, s19
	s_nop 0
	global_load_lds_dwordx4 v[0:1], off
	s_mov_b32 m0, s10
	v_lshl_add_u64 v[0:1], v[198:199], 0, s[94:95]
	s_add_i32 s21, s19, 0x2000
	s_mov_b32 s10, m0
	s_mov_b32 m0, s21
	s_nop 0
	global_load_lds_dwordx4 v[0:1], off
	s_mov_b32 m0, s10
	s_mov_b64 s[10:11], 0x160800
	v_lshl_add_u64 v[0:1], v[198:199], 0, s[10:11]
	s_add_i32 s10, s19, 0x4000
	s_mov_b32 s11, m0
	s_mov_b32 m0, s10
	s_nop 0
	global_load_lds_dwordx4 v[0:1], off
	s_mov_b32 m0, s11
	s_mov_b64 s[10:11], 0x160880
	v_lshl_add_u64 v[0:1], v[198:199], 0, s[10:11]
	s_add_i32 s10, s19, 0x6000
	s_mov_b32 s11, m0
	s_mov_b32 m0, s10
	s_nop 0
	global_load_lds_dwordx4 v[0:1], off
	s_mov_b32 m0, s11
	s_mov_b64 s[10:11], 0x2c0800
	v_lshl_add_u64 v[0:1], v[198:199], 0, s[10:11]
	s_add_i32 s10, s19, 0x8000
	s_mov_b32 s11, m0
	s_mov_b32 m0, s10
	s_nop 0
	global_load_lds_dwordx4 v[0:1], off
	s_mov_b32 m0, s11
	v_ashrrev_i32_e32 v5, 31, v4
	v_lshl_add_u64 v[2:3], v[2:3], 0, s[90:91]
	s_mov_b64 s[10:11], 0x2c0880
	v_lshl_add_u64 v[2:3], v[4:5], 1, v[2:3]
	v_lshl_add_u64 v[0:1], v[198:199], 0, s[10:11]
	s_add_i32 s10, s19, 0xa000
	s_mov_b32 s11, m0
	s_mov_b32 m0, s10
	s_nop 0
	global_load_lds_dwordx4 v[0:1], off
	s_mov_b32 m0, s11
	s_add_i32 s20, s24, 0
	v_lshl_add_u64 v[200:201], v[2:3], 0, s[98:99]
	s_add_i32 s10, s20, 0xc000
	s_mov_b32 s11, m0
	s_mov_b32 m0, s10
	s_nop 0
	global_load_lds_dwordx4 v[200:201], off
	s_mov_b32 m0, s11
	s_mov_b64 s[10:11], 0x59000
	v_lshl_add_u64 v[0:1], v[2:3], 0, s[10:11]
	s_add_i32 s10, s20, 0xc400
	s_mov_b32 s11, m0
	s_mov_b32 m0, s10
	s_nop 0
	global_load_lds_dwordx4 v[0:1], off
	s_mov_b32 m0, s11
	s_mov_b64 s[10:11], 0x161000
	v_lshl_add_u64 v[0:1], v[2:3], 0, s[10:11]
	s_add_i32 s10, s20, 0x10000
	s_mov_b32 s11, m0
	s_mov_b32 m0, s10
	s_nop 0
	global_load_lds_dwordx4 v[0:1], off
	s_mov_b32 m0, s11
	s_mov_b64 s[10:11], 0x1b9000
	v_lshl_add_u64 v[0:1], v[2:3], 0, s[10:11]
	s_add_i32 s20, s20, 0x10400
	s_mov_b32 s10, m0
	s_mov_b32 m0, s20
	s_nop 0
	global_load_lds_dwordx4 v[0:1], off
	s_mov_b32 m0, s10
	s_waitcnt vmcnt(0)
	s_barrier
	v_add_u32_e32 v44, 0, v204
	ds_read_b128 v[0:3], v44
	ds_read_b128 v[4:7], v44 offset:4096
	s_waitcnt vmcnt(3) lgkmcnt(1)
	v_mfma_f32_32x32x16_bf16 v[16:31], v[0:3], v[130:133], 0
	v_bfe_u32 v45, v40, 1, 3
	v_bitop3_b32 v0, v41, v45, 2 bitop3:0x36
	v_lshl_or_b32 v128, v0, 4, v43
	v_add_u32_e32 v46, 0, v128
	ds_read_b128 v[32:35], v46
	ds_read_b128 v[36:39], v46 offset:4096
	v_lshlrev_b32_e32 v203, 2, v41
	s_mov_b64 s[22:23], 0x420800
	s_waitcnt lgkmcnt(2)
	v_mfma_f32_32x32x16_bf16 v[0:15], v[4:7], v[130:133], 0
	v_mov_b32_e32 v209, 0
	v_and_b32_e32 v202, 63, v40
	v_ashrrev_i32_e32 v195, 31, v194
	s_movk_i32 s10, 0x4000
	s_mov_b32 s11, 0x8000
	s_mov_b32 s20, 0
	s_mov_b32 s33, 0
	s_waitcnt vmcnt(2) lgkmcnt(1)
	v_mfma_f32_32x32x16_bf16 v[16:31], v[32:35], v[134:137], v[16:31]
	v_bitop3_b32 v32, v41, v45, 4 bitop3:0x36
	v_lshl_or_b32 v205, v32, 4, v43
	v_add_u32_e32 v47, 0, v205
	v_mov_b32_e32 v48, 0
	v_mov_b32_e32 v49, v209
	v_mov_b32_e32 v50, v209
	v_mov_b32_e32 v51, v209
	s_waitcnt lgkmcnt(0)
	v_mfma_f32_32x32x16_bf16 v[0:15], v[36:39], v[134:137], v[0:15]
	ds_read_b128 v[32:35], v47
	ds_read_b128 v[36:39], v47 offset:4096
	v_mov_b32_e32 v52, v209
	v_mov_b32_e32 v53, v209
	v_mov_b32_e32 v54, v209
	v_mov_b32_e32 v55, v209
	v_mov_b32_e32 v56, v209
	v_mov_b32_e32 v57, v209
	s_waitcnt vmcnt(1) lgkmcnt(1)
	v_mfma_f32_32x32x16_bf16 v[16:31], v[32:35], v[138:141], v[16:31]
	v_bitop3_b32 v32, v41, v45, 6 bitop3:0x36
	v_lshl_or_b32 v206, v32, 4, v43
	v_add_u32_e32 v43, 0, v206
	ds_read_b128 v[32:35], v43
	v_mov_b32_e32 v45, v209
	v_mov_b32_e32 v58, v209
	v_mov_b32_e32 v59, v209
	s_waitcnt lgkmcnt(1)
	v_mfma_f32_32x32x16_bf16 v[0:15], v[36:39], v[138:141], v[0:15]
	v_lshrrev_b32_e32 v36, 2, v40
	v_and_or_b32 v41, v36, 3, v203
	ds_read_b128 v[36:39], v43 offset:4096
	ds_read_b128 v[100:103], v44 offset:16384
	ds_read_b128 v[96:99], v44 offset:20480
	ds_read_b128 v[182:185], v46 offset:16384
	ds_read_b128 v[178:181], v46 offset:20480
	ds_read_b128 v[174:177], v47 offset:16384
	ds_read_b128 v[170:173], v47 offset:20480
	ds_read_b128 v[166:169], v43 offset:16384
	ds_read_b128 v[162:165], v43 offset:20480
	s_waitcnt lgkmcnt(0)
	s_barrier
	v_mov_b32_e32 v43, v209
	v_mov_b32_e32 v44, v209
	s_waitcnt vmcnt(0) lgkmcnt(9)
	v_mfma_f32_32x32x16_bf16 v[16:31], v[32:35], v[142:145], v[16:31]
	v_lshlrev_b32_e32 v33, 1, v40
	v_lshlrev_b32_e32 v32, 6, v41
	v_and_b32_e32 v33, 32, v33
	v_or3_b32 v207, v32, v33, v42
	v_lshl_add_u64 v[32:33], v[198:199], 0, s[22:23]
	s_mov_b32 s22, m0
	s_mov_b32 m0, s19
	s_nop 0
	global_load_lds_dwordx4 v[32:33], off
	s_mov_b32 m0, s22
	s_mov_b64 s[22:23], 0x420880
	s_waitcnt lgkmcnt(8)
	v_mfma_f32_32x32x16_bf16 v[0:15], v[36:39], v[142:145], v[0:15]
	s_nop 3
	v_exp_f32_e32 v80, v16
	v_exp_f32_e32 v81, v17
	v_exp_f32_e32 v82, v18
	v_exp_f32_e32 v83, v19
	v_exp_f32_e32 v84, v20
	v_exp_f32_e32 v85, v21
	v_exp_f32_e32 v86, v22
	v_exp_f32_e32 v87, v23
	v_exp_f32_e32 v88, v24
	v_exp_f32_e32 v89, v25
	v_exp_f32_e32 v90, v26
	v_exp_f32_e32 v91, v27
	v_exp_f32_e32 v92, v28
	v_exp_f32_e32 v93, v29
	v_exp_f32_e32 v94, v30
	v_exp_f32_e32 v95, v31
	v_exp_f32_e32 v64, v0
	v_exp_f32_e32 v65, v1
	v_exp_f32_e32 v66, v2
	v_exp_f32_e32 v67, v3
	v_exp_f32_e32 v68, v4
	v_exp_f32_e32 v69, v5
	v_exp_f32_e32 v70, v6
	v_exp_f32_e32 v71, v7
	v_exp_f32_e32 v72, v8
	v_exp_f32_e32 v73, v9
	v_exp_f32_e32 v74, v10
	v_exp_f32_e32 v75, v11
	v_exp_f32_e32 v76, v12
	v_exp_f32_e32 v77, v13
	v_exp_f32_e32 v78, v14
	v_exp_f32_e32 v79, v15
	v_lshl_add_u64 v[32:33], v[198:199], 0, s[22:23]
	s_mov_b32 s19, m0
	s_mov_b32 m0, s21
	s_nop 0
	global_load_lds_dwordx4 v[32:33], off
	s_mov_b32 m0, s19
	v_add_u32_e32 v208, 0, v207
	s_add_i32 s19, s4, -1
	s_add_i32 s21, s5, 0x2000
	s_add_i32 s22, s24, 0xc000
	v_mov_b32_e32 v0, 0
	v_mov_b32_e32 v1, v209
	v_mov_b32_e32 v2, v209
	v_mov_b32_e32 v3, v209
	v_mov_b32_e32 v4, v209
	v_mov_b32_e32 v5, v209
	v_mov_b32_e32 v6, v209
	v_mov_b32_e32 v7, v209
	v_mov_b32_e32 v8, v209
	v_mov_b32_e32 v9, v209
	v_mov_b32_e32 v10, v209
	v_mov_b32_e32 v11, v209
	v_mov_b32_e32 v12, v209
	v_mov_b32_e32 v13, v209
	v_mov_b32_e32 v14, v209
	v_mov_b32_e32 v15, v209
	v_mov_b32_e32 v16, 0
	v_mov_b32_e32 v17, v209
	v_mov_b32_e32 v18, v209
	v_mov_b32_e32 v19, v209
	v_mov_b32_e32 v20, v209
	v_mov_b32_e32 v21, v209
	v_mov_b32_e32 v22, v209
	v_mov_b32_e32 v23, v209
	v_mov_b32_e32 v24, v209
	v_mov_b32_e32 v25, v209
	v_mov_b32_e32 v26, v209
	v_mov_b32_e32 v27, v209
	v_mov_b32_e32 v28, v209
	v_mov_b32_e32 v29, v209
	v_mov_b32_e32 v30, v209
	v_mov_b32_e32 v31, v209
	v_mov_b32_e32 v32, 0
	v_mov_b32_e32 v33, v209
	v_mov_b32_e32 v34, v209
	v_mov_b32_e32 v35, v209
	v_mov_b32_e32 v36, v209
	v_mov_b32_e32 v37, v209
	v_mov_b32_e32 v38, v209
	v_mov_b32_e32 v39, v209
	v_mov_b32_e32 v40, v209
	v_mov_b32_e32 v41, v209
	v_mov_b32_e32 v42, v209
	v_mov_b32_e32 v46, v209
	v_mov_b32_e32 v47, v209
	v_mov_b32_e32 v60, v209
	v_mov_b32_e32 v61, v209
	v_mov_b32_e32 v62, v209
	v_mov_b32_e32 v63, v209
	v_readfirstlane_b32 s44, v198
	v_readfirstlane_b32 s45, v199
	s_nop 1
	s_sub_u32 s44, s44, 0x200000
	s_subb_u32 s45, s45, 0
	s_add_i32 s32, s21, 0xffffff80
	v_subrev_u32_e32 v199, s44, v198
	v_add_u32_e32 v199, 0x800, v199
	v_subrev_u32_e32 v201, s44, v200
	v_add_u32_e32 v207, 0xc000, v207
.LBB0_86:
	s_add_i32 s24, s33, 2
	v_mfma_f32_32x32x16_bf16 v[112:127], v[100:103], v[130:133], 0
	v_add_f32_e32 v100, v82, v80
	v_add_f32_e32 v101, v83, v81
	v_cvt_pk_bf16_f32 v158, v80, v81
	v_cvt_pk_bf16_f32 v159, v82, v83
	v_add_f32_e32 v80, v84, v100
	v_add_f32_e32 v81, v85, v101
	v_add_f32_e32 v146, v86, v80
	v_cvt_pk_bf16_f32 v160, v84, v85
	v_mfma_f32_32x32x16_bf16 v[96:111], v[96:99], v[130:133], 0
	v_add_f32_e32 v84, v87, v81
	v_cvt_pk_bf16_f32 v161, v86, v87
	ds_read_b64_tr_b16 v[80:81], v207 offset:0
	ds_read_b64_tr_b16 v[82:83], v207 offset:512
	v_add_f32_e32 v85, v88, v146
	v_add_f32_e32 v84, v89, v84
	v_mfma_f32_32x32x16_bf16 v[112:127], v[182:185], v[134:137], v[112:127]
	v_add_f32_e32 v146, v90, v85
	v_add_f32_e32 v147, v91, v84
	v_cvt_pk_bf16_f32 v154, v88, v89
	v_cvt_pk_bf16_f32 v155, v90, v91
	ds_read_b64_tr_b16 v[84:85], v207 offset:4096
	ds_read_b64_tr_b16 v[86:87], v207 offset:4608
	v_add_f32_e32 v88, v92, v146
	v_add_f32_e32 v89, v93, v147
	v_mfma_f32_32x32x16_bf16 v[96:111], v[178:181], v[134:137], v[96:111]
	v_add_f32_e32 v146, v94, v88
	v_add_f32_e32 v147, v95, v89
	v_cvt_pk_bf16_f32 v156, v92, v93
	v_cvt_pk_bf16_f32 v157, v94, v95
	ds_read_b64_tr_b16 v[88:89], v207 offset:8192
	ds_read_b64_tr_b16 v[90:91], v207 offset:8704
	v_add_f32_e32 v92, v64, v146
	v_add_f32_e32 v93, v65, v147
	v_mfma_f32_32x32x16_bf16 v[112:127], v[174:177], v[138:141], v[112:127]
	v_add_f32_e32 v92, v66, v92
	v_add_f32_e32 v93, v67, v93
	v_cvt_pk_bf16_f32 v150, v64, v65
	v_cvt_pk_bf16_f32 v151, v66, v67
	ds_read_b64_tr_b16 v[64:65], v207 offset:12288
	ds_read_b64_tr_b16 v[66:67], v207 offset:12800
	v_add_f32_e32 v92, v68, v92
	v_add_f32_e32 v93, v69, v93
	v_mfma_f32_32x32x16_bf16 v[96:111], v[170:173], v[138:141], v[96:111]
	v_add_f32_e32 v92, v70, v92
	v_add_f32_e32 v93, v71, v93
	v_cvt_pk_bf16_f32 v152, v68, v69
	v_cvt_pk_bf16_f32 v153, v70, v71
	v_add_f32_e32 v68, v72, v92
	v_add_f32_e32 v69, v73, v93
	v_mfma_f32_32x32x16_bf16 v[112:127], v[166:169], v[142:145], v[112:127]
	v_add_f32_e32 v68, v74, v68
	v_add_f32_e32 v69, v75, v69
	v_cvt_pk_bf16_f32 v146, v72, v73
	v_cvt_pk_bf16_f32 v147, v74, v75
	v_add_f32_e32 v68, v76, v68
	v_add_f32_e32 v69, v77, v69
	v_mfma_f32_32x32x16_bf16 v[96:111], v[162:165], v[142:145], v[96:111]
	v_add_f32_e32 v68, v78, v68
	v_add_f32_e32 v69, v79, v69
	v_cvt_pk_bf16_f32 v148, v76, v77
	v_cvt_pk_bf16_f32 v149, v78, v79
	s_nop 0
	v_exp_f32_e32 v112, v112
	v_exp_f32_e32 v113, v113
	s_waitcnt lgkmcnt(4)
	v_mfma_f32_32x32x16_bf16 v[48:63], v[80:83], v[158:161], v[48:63]
	v_add_f32_e32 v92, v68, v69
	ds_read_b64_tr_b16 v[68:69], v207 offset:1024
	ds_read_b64_tr_b16 v[70:71], v207 offset:1536
	v_exp_f32_e32 v114, v114
	v_exp_f32_e32 v115, v115
	v_mfma_f32_32x32x16_bf16 v[32:47], v[84:87], v[158:161], v[32:47]
	ds_read_b64_tr_b16 v[72:73], v207 offset:5120
	ds_read_b64_tr_b16 v[74:75], v207 offset:5632
	v_exp_f32_e32 v116, v116
	v_exp_f32_e32 v117, v117
	s_waitcnt lgkmcnt(4)
	v_mfma_f32_32x32x16_bf16 v[16:31], v[88:91], v[158:161], v[16:31]
	s_add_i32 s90, s33, 4
	s_min_u32 s90, s90, s19
	s_mul_i32 s90, s90, 0x160000
	s_add_i32 m0, s5, 0x4000
	s_add_u32 s100, s44, s90
	s_addc_u32 s101, s45, 0
	global_load_lds_dwordx4 v199, s[100:101]
	ds_read_b64_tr_b16 v[76:77], v207 offset:9216
	ds_read_b64_tr_b16 v[78:79], v207 offset:9728
	v_exp_f32_e32 v118, v118
	v_exp_f32_e32 v119, v119
	v_mfma_f32_32x32x16_bf16 v[0:15], v[64:67], v[158:161], v[0:15]
	ds_read_b64_tr_b16 v[80:81], v207 offset:13312
	ds_read_b64_tr_b16 v[82:83], v207 offset:13824
	v_exp_f32_e32 v120, v120
	v_exp_f32_e32 v121, v121
	s_waitcnt lgkmcnt(4)
	v_mfma_f32_32x32x16_bf16 v[48:63], v[68:71], v[154:157], v[48:63]
	ds_read_b64_tr_b16 v[84:85], v207 offset:2048
	ds_read_b64_tr_b16 v[86:87], v207 offset:2560
	ds_read_b128 v[68:71], v204 offset:32768
	v_exp_f32_e32 v122, v122
	v_exp_f32_e32 v123, v123
	v_mfma_f32_32x32x16_bf16 v[32:47], v[72:75], v[154:157], v[32:47]
	ds_read_b64_tr_b16 v[72:73], v207 offset:6144
	ds_read_b64_tr_b16 v[74:75], v207 offset:6656
	ds_read_b128 v[64:67], v204 offset:36864
	v_exp_f32_e32 v124, v124
	v_exp_f32_e32 v125, v125
	s_waitcnt lgkmcnt(6)
	v_mfma_f32_32x32x16_bf16 v[16:31], v[76:79], v[154:157], v[16:31]
	s_add_i32 m0, s32, 0x4000
	s_nop 0
	global_load_lds_dwordx4 v199, s[100:101] offset:128
	ds_read_b64_tr_b16 v[76:77], v207 offset:10240
	ds_read_b64_tr_b16 v[78:79], v207 offset:10752
	ds_read_b128 v[182:185], v128 offset:32768
	v_exp_f32_e32 v126, v126
	v_exp_f32_e32 v127, v127
	v_mfma_f32_32x32x16_bf16 v[0:15], v[80:83], v[154:157], v[0:15]
	ds_read_b64_tr_b16 v[80:81], v207 offset:14336
	ds_read_b64_tr_b16 v[82:83], v207 offset:14848
	ds_read_b128 v[178:181], v128 offset:36864
	v_exp_f32_e32 v96, v96
	v_exp_f32_e32 v97, v97
	s_waitcnt lgkmcnt(7)
	v_mfma_f32_32x32x16_bf16 v[48:63], v[84:87], v[150:153], v[48:63]
	ds_read_b64_tr_b16 v[84:85], v207 offset:3072
	ds_read_b64_tr_b16 v[86:87], v207 offset:3584
	ds_read_b128 v[174:177], v205 offset:32768
	v_exp_f32_e32 v98, v98
	v_exp_f32_e32 v99, v99
	v_mfma_f32_32x32x16_bf16 v[32:47], v[72:75], v[150:153], v[32:47]
	ds_read_b64_tr_b16 v[72:73], v207 offset:7168
	ds_read_b64_tr_b16 v[74:75], v207 offset:7680
	ds_read_b128 v[170:173], v205 offset:36864
	v_exp_f32_e32 v100, v100
	v_exp_f32_e32 v101, v101
	s_waitcnt lgkmcnt(7)
	v_mfma_f32_32x32x16_bf16 v[16:31], v[76:79], v[150:153], v[16:31]
	s_min_u32 s90, s24, s19
	s_mul_i32 s90, s90, 0x160000
	s_add_i32 m0, s22, 0x8000
	s_add_u32 s100, s44, s90
	s_addc_u32 s101, s45, 0
	global_load_lds_dwordx4 v201, s[100:101]
	ds_read_b64_tr_b16 v[76:77], v207 offset:11264
	ds_read_b64_tr_b16 v[78:79], v207 offset:11776
	ds_read_b128 v[166:169], v206 offset:32768
	v_exp_f32_e32 v102, v102
	v_exp_f32_e32 v103, v103
	v_mfma_f32_32x32x16_bf16 v[0:15], v[80:83], v[150:153], v[0:15]
	ds_read_b64_tr_b16 v[80:81], v207 offset:15360
	ds_read_b64_tr_b16 v[82:83], v207 offset:15872
	ds_read_b128 v[162:165], v206 offset:36864
	v_exp_f32_e32 v104, v104
	v_exp_f32_e32 v105, v105
	s_waitcnt lgkmcnt(7)
	v_mfma_f32_32x32x16_bf16 v[48:63], v[84:87], v[146:149], v[48:63]
	v_exp_f32_e32 v106, v106
	v_exp_f32_e32 v107, v107
	v_mfma_f32_32x32x16_bf16 v[32:47], v[72:75], v[146:149], v[32:47]
	v_exp_f32_e32 v108, v108
	v_exp_f32_e32 v109, v109
	s_waitcnt lgkmcnt(1)
	v_mfma_f32_32x32x16_bf16 v[16:31], v[76:79], v[146:149], v[16:31]
	s_add_i32 m0, s22, 0x8000
	s_addk_i32 m0, 0x400
	s_add_u32 s100, s100, 0x58000
	s_addc_u32 s101, s101, 0
	global_load_lds_dwordx4 v201, s[100:101]
	v_exp_f32_e32 v110, v110
	v_exp_f32_e32 v111, v111
	v_mfma_f32_32x32x16_bf16 v[0:15], v[80:83], v[146:149], v[0:15]
	s_waitcnt vmcnt(4) lgkmcnt(0)
	s_barrier
	v_add_f32_e32 v186, v209, v92
	v_mfma_f32_32x32x16_bf16 v[80:95], v[68:71], v[130:133], 0
	v_add_f32_e32 v68, v114, v112
	v_add_f32_e32 v69, v115, v113
	v_cvt_pk_bf16_f32 v158, v112, v113
	v_cvt_pk_bf16_f32 v159, v114, v115
	v_add_f32_e32 v68, v116, v68
	v_add_f32_e32 v112, v117, v69
	v_add_f32_e32 v146, v118, v68
	v_cvt_pk_bf16_f32 v160, v116, v117
	v_mfma_f32_32x32x16_bf16 v[64:79], v[64:67], v[130:133], 0
	v_add_f32_e32 v116, v119, v112
	v_cvt_pk_bf16_f32 v161, v118, v119
	ds_read_b64_tr_b16 v[112:113], v207 offset:16384
	ds_read_b64_tr_b16 v[114:115], v207 offset:16896
	v_add_f32_e32 v117, v120, v146
	v_add_f32_e32 v116, v121, v116
	v_mfma_f32_32x32x16_bf16 v[80:95], v[182:185], v[134:137], v[80:95]
	v_add_f32_e32 v146, v122, v117
	v_add_f32_e32 v147, v123, v116
	v_cvt_pk_bf16_f32 v154, v120, v121
	v_cvt_pk_bf16_f32 v155, v122, v123
	ds_read_b64_tr_b16 v[116:117], v207 offset:20480
	ds_read_b64_tr_b16 v[118:119], v207 offset:20992
	v_add_f32_e32 v120, v124, v146
	v_add_f32_e32 v121, v125, v147
	v_mfma_f32_32x32x16_bf16 v[64:79], v[178:181], v[134:137], v[64:79]
	v_add_f32_e32 v146, v126, v120
	v_add_f32_e32 v147, v127, v121
	v_cvt_pk_bf16_f32 v156, v124, v125
	v_cvt_pk_bf16_f32 v157, v126, v127
	ds_read_b64_tr_b16 v[120:121], v207 offset:24576
	ds_read_b64_tr_b16 v[122:123], v207 offset:25088
	v_add_f32_e32 v124, v96, v146
	v_add_f32_e32 v125, v97, v147
	v_mfma_f32_32x32x16_bf16 v[80:95], v[174:177], v[138:141], v[80:95]
	v_add_f32_e32 v124, v98, v124
	v_add_f32_e32 v125, v99, v125
	v_cvt_pk_bf16_f32 v150, v96, v97
	v_cvt_pk_bf16_f32 v151, v98, v99
	ds_read_b64_tr_b16 v[96:97], v207 offset:28672
	ds_read_b64_tr_b16 v[98:99], v207 offset:29184
	v_add_f32_e32 v124, v100, v124
	v_add_f32_e32 v125, v101, v125
	v_mfma_f32_32x32x16_bf16 v[64:79], v[170:173], v[138:141], v[64:79]
	v_add_f32_e32 v124, v102, v124
	v_add_f32_e32 v125, v103, v125
	v_cvt_pk_bf16_f32 v152, v100, v101
	v_cvt_pk_bf16_f32 v153, v102, v103
	v_add_f32_e32 v100, v104, v124
	v_add_f32_e32 v101, v105, v125
	v_mfma_f32_32x32x16_bf16 v[80:95], v[166:169], v[142:145], v[80:95]
	v_add_f32_e32 v100, v106, v100
	v_add_f32_e32 v101, v107, v101
	v_cvt_pk_bf16_f32 v146, v104, v105
	v_cvt_pk_bf16_f32 v147, v106, v107
	v_add_f32_e32 v100, v108, v100
	v_add_f32_e32 v101, v109, v101
	v_mfma_f32_32x32x16_bf16 v[64:79], v[162:165], v[142:145], v[64:79]
	v_add_f32_e32 v100, v110, v100
	v_add_f32_e32 v101, v111, v101
	v_cvt_pk_bf16_f32 v148, v108, v109
	v_cvt_pk_bf16_f32 v149, v110, v111
	v_add_f32_e32 v100, v100, v101
	v_exp_f32_e32 v80, v80
	v_exp_f32_e32 v81, v81
	s_waitcnt lgkmcnt(4)
	v_mfma_f32_32x32x16_bf16 v[48:63], v[112:115], v[158:161], v[48:63]
	v_add_f32_e32 v209, v186, v100
	ds_read_b64_tr_b16 v[100:101], v207 offset:17408
	ds_read_b64_tr_b16 v[102:103], v207 offset:17920
	v_exp_f32_e32 v82, v82
	v_exp_f32_e32 v83, v83
	v_mfma_f32_32x32x16_bf16 v[32:47], v[116:119], v[158:161], v[32:47]
	ds_read_b64_tr_b16 v[104:105], v207 offset:21504
	ds_read_b64_tr_b16 v[106:107], v207 offset:22016
	v_exp_f32_e32 v84, v84
	v_exp_f32_e32 v85, v85
	s_waitcnt lgkmcnt(4)
	v_mfma_f32_32x32x16_bf16 v[16:31], v[120:123], v[158:161], v[16:31]
	s_add_i32 s90, s33, 5
	s_min_u32 s90, s90, s19
	s_mul_i32 s90, s90, 0x160000
	s_add_i32 m0, s5, 0x8000
	s_add_u32 s100, s44, s90
	s_addc_u32 s101, s45, 0
	global_load_lds_dwordx4 v199, s[100:101]
	ds_read_b64_tr_b16 v[108:109], v207 offset:25600
	ds_read_b64_tr_b16 v[110:111], v207 offset:26112
	v_exp_f32_e32 v86, v86
	v_exp_f32_e32 v87, v87
	v_mfma_f32_32x32x16_bf16 v[0:15], v[96:99], v[158:161], v[0:15]
	ds_read_b64_tr_b16 v[112:113], v207 offset:29696
	ds_read_b64_tr_b16 v[114:115], v207 offset:30208
	v_exp_f32_e32 v88, v88
	v_exp_f32_e32 v89, v89
	s_waitcnt lgkmcnt(4)
	v_mfma_f32_32x32x16_bf16 v[48:63], v[100:103], v[154:157], v[48:63]
	ds_read_b64_tr_b16 v[116:117], v207 offset:18432
	ds_read_b64_tr_b16 v[118:119], v207 offset:18944
	ds_read_b128 v[100:103], v204
	v_exp_f32_e32 v90, v90
	v_exp_f32_e32 v91, v91
	v_mfma_f32_32x32x16_bf16 v[32:47], v[104:107], v[154:157], v[32:47]
	ds_read_b64_tr_b16 v[104:105], v207 offset:22528
	ds_read_b64_tr_b16 v[106:107], v207 offset:23040
	ds_read_b128 v[96:99], v204 offset:4096
	v_exp_f32_e32 v92, v92
	v_exp_f32_e32 v93, v93
	s_waitcnt lgkmcnt(6)
	v_mfma_f32_32x32x16_bf16 v[16:31], v[108:111], v[154:157], v[16:31]
	s_add_i32 m0, s32, 0x8000
	s_nop 0
	global_load_lds_dwordx4 v199, s[100:101] offset:128
	ds_read_b64_tr_b16 v[108:109], v207 offset:26624
	ds_read_b64_tr_b16 v[110:111], v207 offset:27136
	ds_read_b128 v[182:185], v128
	v_exp_f32_e32 v94, v94
	v_exp_f32_e32 v95, v95
	v_mfma_f32_32x32x16_bf16 v[0:15], v[112:115], v[154:157], v[0:15]
	ds_read_b64_tr_b16 v[112:113], v207 offset:30720
	ds_read_b64_tr_b16 v[114:115], v207 offset:31232
	ds_read_b128 v[178:181], v128 offset:4096
	v_exp_f32_e32 v64, v64
	v_exp_f32_e32 v65, v65
	s_waitcnt lgkmcnt(7)
	v_mfma_f32_32x32x16_bf16 v[48:63], v[116:119], v[150:153], v[48:63]
	ds_read_b64_tr_b16 v[116:117], v207 offset:19456
	ds_read_b64_tr_b16 v[118:119], v207 offset:19968
	ds_read_b128 v[174:177], v205
	v_exp_f32_e32 v66, v66
	v_exp_f32_e32 v67, v67
	v_mfma_f32_32x32x16_bf16 v[32:47], v[104:107], v[150:153], v[32:47]
	ds_read_b64_tr_b16 v[104:105], v207 offset:23552
	ds_read_b64_tr_b16 v[106:107], v207 offset:24064
	ds_read_b128 v[170:173], v205 offset:4096
	v_exp_f32_e32 v68, v68
	v_exp_f32_e32 v69, v69
	s_waitcnt lgkmcnt(7)
	v_mfma_f32_32x32x16_bf16 v[16:31], v[108:111], v[150:153], v[16:31]
	s_add_i32 s90, s33, 3
	s_min_u32 s90, s90, s19
	s_mul_i32 s90, s90, 0x160000
	s_add_i32 m0, s22, 0x0
	s_add_u32 s100, s44, s90
	s_addc_u32 s101, s45, 0
	global_load_lds_dwordx4 v201, s[100:101]
	ds_read_b64_tr_b16 v[108:109], v207 offset:27648
	ds_read_b64_tr_b16 v[110:111], v207 offset:28160
	ds_read_b128 v[166:169], v206
	v_exp_f32_e32 v70, v70
	v_exp_f32_e32 v71, v71
	v_mfma_f32_32x32x16_bf16 v[0:15], v[112:115], v[150:153], v[0:15]
	ds_read_b64_tr_b16 v[112:113], v207 offset:31744
	ds_read_b64_tr_b16 v[114:115], v207 offset:32256
	ds_read_b128 v[162:165], v206 offset:4096
	v_exp_f32_e32 v72, v72
	v_exp_f32_e32 v73, v73
	s_waitcnt lgkmcnt(7)
	v_mfma_f32_32x32x16_bf16 v[48:63], v[116:119], v[146:149], v[48:63]
	v_exp_f32_e32 v74, v74
	v_exp_f32_e32 v75, v75
	v_mfma_f32_32x32x16_bf16 v[32:47], v[104:107], v[146:149], v[32:47]
	v_exp_f32_e32 v76, v76
	v_exp_f32_e32 v77, v77
	s_waitcnt lgkmcnt(1)
	v_mfma_f32_32x32x16_bf16 v[16:31], v[108:111], v[146:149], v[16:31]
	s_add_i32 m0, s22, 0x0
	s_addk_i32 m0, 0x400
	s_add_u32 s100, s100, 0x58000
	s_addc_u32 s101, s101, 0
	global_load_lds_dwordx4 v201, s[100:101]
	v_exp_f32_e32 v78, v78
	v_exp_f32_e32 v79, v79
	v_mfma_f32_32x32x16_bf16 v[0:15], v[112:115], v[146:149], v[0:15]
	s_waitcnt vmcnt(4) lgkmcnt(0)
	s_barrier
	s_cmp_ge_u32 s24, s4
	s_mov_b32 s33, s24
	s_cbranch_scc1 .Lattn_done
	s_add_i32 s24, s33, 2
	v_mfma_f32_32x32x16_bf16 v[112:127], v[100:103], v[130:133], 0
	v_add_f32_e32 v100, v82, v80
	v_add_f32_e32 v101, v83, v81
	v_cvt_pk_bf16_f32 v158, v80, v81
	v_cvt_pk_bf16_f32 v159, v82, v83
	v_add_f32_e32 v80, v84, v100
	v_add_f32_e32 v81, v85, v101
	v_add_f32_e32 v146, v86, v80
	v_cvt_pk_bf16_f32 v160, v84, v85
	v_mfma_f32_32x32x16_bf16 v[96:111], v[96:99], v[130:133], 0
	v_add_f32_e32 v84, v87, v81
	v_cvt_pk_bf16_f32 v161, v86, v87
	ds_read_b64_tr_b16 v[80:81], v207 offset:32768
	ds_read_b64_tr_b16 v[82:83], v207 offset:33280
	v_add_f32_e32 v85, v88, v146
	v_add_f32_e32 v84, v89, v84
	v_mfma_f32_32x32x16_bf16 v[112:127], v[182:185], v[134:137], v[112:127]
	v_add_f32_e32 v146, v90, v85
	v_add_f32_e32 v147, v91, v84
	v_cvt_pk_bf16_f32 v154, v88, v89
	v_cvt_pk_bf16_f32 v155, v90, v91
	ds_read_b64_tr_b16 v[84:85], v207 offset:36864
	ds_read_b64_tr_b16 v[86:87], v207 offset:37376
	v_add_f32_e32 v88, v92, v146
	v_add_f32_e32 v89, v93, v147
	v_mfma_f32_32x32x16_bf16 v[96:111], v[178:181], v[134:137], v[96:111]
	v_add_f32_e32 v146, v94, v88
	v_add_f32_e32 v147, v95, v89
	v_cvt_pk_bf16_f32 v156, v92, v93
	v_cvt_pk_bf16_f32 v157, v94, v95
	ds_read_b64_tr_b16 v[88:89], v207 offset:40960
	ds_read_b64_tr_b16 v[90:91], v207 offset:41472
	v_add_f32_e32 v92, v64, v146
	v_add_f32_e32 v93, v65, v147
	v_mfma_f32_32x32x16_bf16 v[112:127], v[174:177], v[138:141], v[112:127]
	v_add_f32_e32 v92, v66, v92
	v_add_f32_e32 v93, v67, v93
	v_cvt_pk_bf16_f32 v150, v64, v65
	v_cvt_pk_bf16_f32 v151, v66, v67
	ds_read_b64_tr_b16 v[64:65], v207 offset:45056
	ds_read_b64_tr_b16 v[66:67], v207 offset:45568
	v_add_f32_e32 v92, v68, v92
	v_add_f32_e32 v93, v69, v93
	v_mfma_f32_32x32x16_bf16 v[96:111], v[170:173], v[138:141], v[96:111]
	v_add_f32_e32 v92, v70, v92
	v_add_f32_e32 v93, v71, v93
	v_cvt_pk_bf16_f32 v152, v68, v69
	v_cvt_pk_bf16_f32 v153, v70, v71
	v_add_f32_e32 v68, v72, v92
	v_add_f32_e32 v69, v73, v93
	v_mfma_f32_32x32x16_bf16 v[112:127], v[166:169], v[142:145], v[112:127]
	v_add_f32_e32 v68, v74, v68
	v_add_f32_e32 v69, v75, v69
	v_cvt_pk_bf16_f32 v146, v72, v73
	v_cvt_pk_bf16_f32 v147, v74, v75
	v_add_f32_e32 v68, v76, v68
	v_add_f32_e32 v69, v77, v69
	v_mfma_f32_32x32x16_bf16 v[96:111], v[162:165], v[142:145], v[96:111]
	v_add_f32_e32 v68, v78, v68
	v_add_f32_e32 v69, v79, v69
	v_cvt_pk_bf16_f32 v148, v76, v77
	v_cvt_pk_bf16_f32 v149, v78, v79
	s_nop 0
	v_exp_f32_e32 v112, v112
	v_exp_f32_e32 v113, v113
	s_waitcnt lgkmcnt(4)
	v_mfma_f32_32x32x16_bf16 v[48:63], v[80:83], v[158:161], v[48:63]
	v_add_f32_e32 v92, v68, v69
	ds_read_b64_tr_b16 v[68:69], v207 offset:33792
	ds_read_b64_tr_b16 v[70:71], v207 offset:34304
	v_exp_f32_e32 v114, v114
	v_exp_f32_e32 v115, v115
	v_mfma_f32_32x32x16_bf16 v[32:47], v[84:87], v[158:161], v[32:47]
	ds_read_b64_tr_b16 v[72:73], v207 offset:37888
	ds_read_b64_tr_b16 v[74:75], v207 offset:38400
	v_exp_f32_e32 v116, v116
	v_exp_f32_e32 v117, v117
	s_waitcnt lgkmcnt(4)
	v_mfma_f32_32x32x16_bf16 v[16:31], v[88:91], v[158:161], v[16:31]
	s_add_i32 s90, s33, 4
	s_min_u32 s90, s90, s19
	s_mul_i32 s90, s90, 0x160000
	s_add_i32 m0, s5, 0x0
	s_add_u32 s100, s44, s90
	s_addc_u32 s101, s45, 0
	global_load_lds_dwordx4 v199, s[100:101]
	ds_read_b64_tr_b16 v[76:77], v207 offset:41984
	ds_read_b64_tr_b16 v[78:79], v207 offset:42496
	v_exp_f32_e32 v118, v118
	v_exp_f32_e32 v119, v119
	v_mfma_f32_32x32x16_bf16 v[0:15], v[64:67], v[158:161], v[0:15]
	ds_read_b64_tr_b16 v[80:81], v207 offset:46080
	ds_read_b64_tr_b16 v[82:83], v207 offset:46592
	v_exp_f32_e32 v120, v120
	v_exp_f32_e32 v121, v121
	s_waitcnt lgkmcnt(4)
	v_mfma_f32_32x32x16_bf16 v[48:63], v[68:71], v[154:157], v[48:63]
	ds_read_b64_tr_b16 v[84:85], v207 offset:34816
	ds_read_b64_tr_b16 v[86:87], v207 offset:35328
	ds_read_b128 v[68:71], v204 offset:16384
	v_exp_f32_e32 v122, v122
	v_exp_f32_e32 v123, v123
	v_mfma_f32_32x32x16_bf16 v[32:47], v[72:75], v[154:157], v[32:47]
	ds_read_b64_tr_b16 v[72:73], v207 offset:38912
	ds_read_b64_tr_b16 v[74:75], v207 offset:39424
	ds_read_b128 v[64:67], v204 offset:20480
	v_exp_f32_e32 v124, v124
	v_exp_f32_e32 v125, v125
	s_waitcnt lgkmcnt(6)
	v_mfma_f32_32x32x16_bf16 v[16:31], v[76:79], v[154:157], v[16:31]
	s_add_i32 m0, s32, 0x0
	s_nop 0
	global_load_lds_dwordx4 v199, s[100:101] offset:128
	ds_read_b64_tr_b16 v[76:77], v207 offset:43008
	ds_read_b64_tr_b16 v[78:79], v207 offset:43520
	ds_read_b128 v[182:185], v128 offset:16384
	v_exp_f32_e32 v126, v126
	v_exp_f32_e32 v127, v127
	v_mfma_f32_32x32x16_bf16 v[0:15], v[80:83], v[154:157], v[0:15]
	ds_read_b64_tr_b16 v[80:81], v207 offset:47104
	ds_read_b64_tr_b16 v[82:83], v207 offset:47616
	ds_read_b128 v[178:181], v128 offset:20480
	v_exp_f32_e32 v96, v96
	v_exp_f32_e32 v97, v97
	s_waitcnt lgkmcnt(7)
	v_mfma_f32_32x32x16_bf16 v[48:63], v[84:87], v[150:153], v[48:63]
	ds_read_b64_tr_b16 v[84:85], v207 offset:35840
	ds_read_b64_tr_b16 v[86:87], v207 offset:36352
	ds_read_b128 v[174:177], v205 offset:16384
	v_exp_f32_e32 v98, v98
	v_exp_f32_e32 v99, v99
	v_mfma_f32_32x32x16_bf16 v[32:47], v[72:75], v[150:153], v[32:47]
	ds_read_b64_tr_b16 v[72:73], v207 offset:39936
	ds_read_b64_tr_b16 v[74:75], v207 offset:40448
	ds_read_b128 v[170:173], v205 offset:20480
	v_exp_f32_e32 v100, v100
	v_exp_f32_e32 v101, v101
	s_waitcnt lgkmcnt(7)
	v_mfma_f32_32x32x16_bf16 v[16:31], v[76:79], v[150:153], v[16:31]
	s_min_u32 s90, s24, s19
	s_mul_i32 s90, s90, 0x160000
	s_add_i32 m0, s22, 0x4000
	s_add_u32 s100, s44, s90
	s_addc_u32 s101, s45, 0
	global_load_lds_dwordx4 v201, s[100:101]
	ds_read_b64_tr_b16 v[76:77], v207 offset:44032
	ds_read_b64_tr_b16 v[78:79], v207 offset:44544
	ds_read_b128 v[166:169], v206 offset:16384
	v_exp_f32_e32 v102, v102
	v_exp_f32_e32 v103, v103
	v_mfma_f32_32x32x16_bf16 v[0:15], v[80:83], v[150:153], v[0:15]
	ds_read_b64_tr_b16 v[80:81], v207 offset:48128
	ds_read_b64_tr_b16 v[82:83], v207 offset:48640
	ds_read_b128 v[162:165], v206 offset:20480
	v_exp_f32_e32 v104, v104
	v_exp_f32_e32 v105, v105
	s_waitcnt lgkmcnt(7)
	v_mfma_f32_32x32x16_bf16 v[48:63], v[84:87], v[146:149], v[48:63]
	v_exp_f32_e32 v106, v106
	v_exp_f32_e32 v107, v107
	v_mfma_f32_32x32x16_bf16 v[32:47], v[72:75], v[146:149], v[32:47]
	v_exp_f32_e32 v108, v108
	v_exp_f32_e32 v109, v109
	s_waitcnt lgkmcnt(1)
	v_mfma_f32_32x32x16_bf16 v[16:31], v[76:79], v[146:149], v[16:31]
	s_add_i32 m0, s22, 0x4000
	s_addk_i32 m0, 0x400
	s_add_u32 s100, s100, 0x58000
	s_addc_u32 s101, s101, 0
	global_load_lds_dwordx4 v201, s[100:101]
	v_exp_f32_e32 v110, v110
	v_exp_f32_e32 v111, v111
	v_mfma_f32_32x32x16_bf16 v[0:15], v[80:83], v[146:149], v[0:15]
	s_waitcnt vmcnt(4) lgkmcnt(0)
	s_barrier
	v_add_f32_e32 v186, v209, v92
	v_mfma_f32_32x32x16_bf16 v[80:95], v[68:71], v[130:133], 0
	v_add_f32_e32 v68, v114, v112
	v_add_f32_e32 v69, v115, v113
	v_cvt_pk_bf16_f32 v158, v112, v113
	v_cvt_pk_bf16_f32 v159, v114, v115
	v_add_f32_e32 v68, v116, v68
	v_add_f32_e32 v112, v117, v69
	v_add_f32_e32 v146, v118, v68
	v_cvt_pk_bf16_f32 v160, v116, v117
	v_mfma_f32_32x32x16_bf16 v[64:79], v[64:67], v[130:133], 0
	v_add_f32_e32 v116, v119, v112
	v_cvt_pk_bf16_f32 v161, v118, v119
	ds_read_b64_tr_b16 v[112:113], v207 offset:0
	ds_read_b64_tr_b16 v[114:115], v207 offset:512
	v_add_f32_e32 v117, v120, v146
	v_add_f32_e32 v116, v121, v116
	v_mfma_f32_32x32x16_bf16 v[80:95], v[182:185], v[134:137], v[80:95]
	v_add_f32_e32 v146, v122, v117
	v_add_f32_e32 v147, v123, v116
	v_cvt_pk_bf16_f32 v154, v120, v121
	v_cvt_pk_bf16_f32 v155, v122, v123
	ds_read_b64_tr_b16 v[116:117], v207 offset:4096
	ds_read_b64_tr_b16 v[118:119], v207 offset:4608
	v_add_f32_e32 v120, v124, v146
	v_add_f32_e32 v121, v125, v147
	v_mfma_f32_32x32x16_bf16 v[64:79], v[178:181], v[134:137], v[64:79]
	v_add_f32_e32 v146, v126, v120
	v_add_f32_e32 v147, v127, v121
	v_cvt_pk_bf16_f32 v156, v124, v125
	v_cvt_pk_bf16_f32 v157, v126, v127
	ds_read_b64_tr_b16 v[120:121], v207 offset:8192
	ds_read_b64_tr_b16 v[122:123], v207 offset:8704
	v_add_f32_e32 v124, v96, v146
	v_add_f32_e32 v125, v97, v147
	v_mfma_f32_32x32x16_bf16 v[80:95], v[174:177], v[138:141], v[80:95]
	v_add_f32_e32 v124, v98, v124
	v_add_f32_e32 v125, v99, v125
	v_cvt_pk_bf16_f32 v150, v96, v97
	v_cvt_pk_bf16_f32 v151, v98, v99
	ds_read_b64_tr_b16 v[96:97], v207 offset:12288
	ds_read_b64_tr_b16 v[98:99], v207 offset:12800
	v_add_f32_e32 v124, v100, v124
	v_add_f32_e32 v125, v101, v125
	v_mfma_f32_32x32x16_bf16 v[64:79], v[170:173], v[138:141], v[64:79]
	v_add_f32_e32 v124, v102, v124
	v_add_f32_e32 v125, v103, v125
	v_cvt_pk_bf16_f32 v152, v100, v101
	v_cvt_pk_bf16_f32 v153, v102, v103
	v_add_f32_e32 v100, v104, v124
	v_add_f32_e32 v101, v105, v125
	v_mfma_f32_32x32x16_bf16 v[80:95], v[166:169], v[142:145], v[80:95]
	v_add_f32_e32 v100, v106, v100
	v_add_f32_e32 v101, v107, v101
	v_cvt_pk_bf16_f32 v146, v104, v105
	v_cvt_pk_bf16_f32 v147, v106, v107
	v_add_f32_e32 v100, v108, v100
	v_add_f32_e32 v101, v109, v101
	v_mfma_f32_32x32x16_bf16 v[64:79], v[162:165], v[142:145], v[64:79]
	v_add_f32_e32 v100, v110, v100
	v_add_f32_e32 v101, v111, v101
	v_cvt_pk_bf16_f32 v148, v108, v109
	v_cvt_pk_bf16_f32 v149, v110, v111
	v_add_f32_e32 v100, v100, v101
	v_exp_f32_e32 v80, v80
	v_exp_f32_e32 v81, v81
	s_waitcnt lgkmcnt(4)
	v_mfma_f32_32x32x16_bf16 v[48:63], v[112:115], v[158:161], v[48:63]
	v_add_f32_e32 v209, v186, v100
	ds_read_b64_tr_b16 v[100:101], v207 offset:1024
	ds_read_b64_tr_b16 v[102:103], v207 offset:1536
	v_exp_f32_e32 v82, v82
	v_exp_f32_e32 v83, v83
	v_mfma_f32_32x32x16_bf16 v[32:47], v[116:119], v[158:161], v[32:47]
	ds_read_b64_tr_b16 v[104:105], v207 offset:5120
	ds_read_b64_tr_b16 v[106:107], v207 offset:5632
	v_exp_f32_e32 v84, v84
	v_exp_f32_e32 v85, v85
	s_waitcnt lgkmcnt(4)
	v_mfma_f32_32x32x16_bf16 v[16:31], v[120:123], v[158:161], v[16:31]
	s_add_i32 s90, s33, 5
	s_min_u32 s90, s90, s19
	s_mul_i32 s90, s90, 0x160000
	s_add_i32 m0, s5, 0x4000
	s_add_u32 s100, s44, s90
	s_addc_u32 s101, s45, 0
	global_load_lds_dwordx4 v199, s[100:101]
	ds_read_b64_tr_b16 v[108:109], v207 offset:9216
	ds_read_b64_tr_b16 v[110:111], v207 offset:9728
	v_exp_f32_e32 v86, v86
	v_exp_f32_e32 v87, v87
	v_mfma_f32_32x32x16_bf16 v[0:15], v[96:99], v[158:161], v[0:15]
	ds_read_b64_tr_b16 v[112:113], v207 offset:13312
	ds_read_b64_tr_b16 v[114:115], v207 offset:13824
	v_exp_f32_e32 v88, v88
	v_exp_f32_e32 v89, v89
	s_waitcnt lgkmcnt(4)
	v_mfma_f32_32x32x16_bf16 v[48:63], v[100:103], v[154:157], v[48:63]
	ds_read_b64_tr_b16 v[116:117], v207 offset:2048
	ds_read_b64_tr_b16 v[118:119], v207 offset:2560
	ds_read_b128 v[100:103], v204 offset:32768
	v_exp_f32_e32 v90, v90
	v_exp_f32_e32 v91, v91
	v_mfma_f32_32x32x16_bf16 v[32:47], v[104:107], v[154:157], v[32:47]
	ds_read_b64_tr_b16 v[104:105], v207 offset:6144
	ds_read_b64_tr_b16 v[106:107], v207 offset:6656
	ds_read_b128 v[96:99], v204 offset:36864
	v_exp_f32_e32 v92, v92
	v_exp_f32_e32 v93, v93
	s_waitcnt lgkmcnt(6)
	v_mfma_f32_32x32x16_bf16 v[16:31], v[108:111], v[154:157], v[16:31]
	s_add_i32 m0, s32, 0x4000
	s_nop 0
	global_load_lds_dwordx4 v199, s[100:101] offset:128
	ds_read_b64_tr_b16 v[108:109], v207 offset:10240
	ds_read_b64_tr_b16 v[110:111], v207 offset:10752
	ds_read_b128 v[182:185], v128 offset:32768
	v_exp_f32_e32 v94, v94
	v_exp_f32_e32 v95, v95
	v_mfma_f32_32x32x16_bf16 v[0:15], v[112:115], v[154:157], v[0:15]
	ds_read_b64_tr_b16 v[112:113], v207 offset:14336
	ds_read_b64_tr_b16 v[114:115], v207 offset:14848
	ds_read_b128 v[178:181], v128 offset:36864
	v_exp_f32_e32 v64, v64
	v_exp_f32_e32 v65, v65
	s_waitcnt lgkmcnt(7)
	v_mfma_f32_32x32x16_bf16 v[48:63], v[116:119], v[150:153], v[48:63]
	ds_read_b64_tr_b16 v[116:117], v207 offset:3072
	ds_read_b64_tr_b16 v[118:119], v207 offset:3584
	ds_read_b128 v[174:177], v205 offset:32768
	v_exp_f32_e32 v66, v66
	v_exp_f32_e32 v67, v67
	v_mfma_f32_32x32x16_bf16 v[32:47], v[104:107], v[150:153], v[32:47]
	ds_read_b64_tr_b16 v[104:105], v207 offset:7168
	ds_read_b64_tr_b16 v[106:107], v207 offset:7680
	ds_read_b128 v[170:173], v205 offset:36864
	v_exp_f32_e32 v68, v68
	v_exp_f32_e32 v69, v69
	s_waitcnt lgkmcnt(7)
	v_mfma_f32_32x32x16_bf16 v[16:31], v[108:111], v[150:153], v[16:31]
	s_add_i32 s90, s33, 3
	s_min_u32 s90, s90, s19
	s_mul_i32 s90, s90, 0x160000
	s_add_i32 m0, s22, 0x8000
	s_add_u32 s100, s44, s90
	s_addc_u32 s101, s45, 0
	global_load_lds_dwordx4 v201, s[100:101]
	ds_read_b64_tr_b16 v[108:109], v207 offset:11264
	ds_read_b64_tr_b16 v[110:111], v207 offset:11776
	ds_read_b128 v[166:169], v206 offset:32768
	v_exp_f32_e32 v70, v70
	v_exp_f32_e32 v71, v71
	v_mfma_f32_32x32x16_bf16 v[0:15], v[112:115], v[150:153], v[0:15]
	ds_read_b64_tr_b16 v[112:113], v207 offset:15360
	ds_read_b64_tr_b16 v[114:115], v207 offset:15872
	ds_read_b128 v[162:165], v206 offset:36864
	v_exp_f32_e32 v72, v72
	v_exp_f32_e32 v73, v73
	s_waitcnt lgkmcnt(7)
	v_mfma_f32_32x32x16_bf16 v[48:63], v[116:119], v[146:149], v[48:63]
	v_exp_f32_e32 v74, v74
	v_exp_f32_e32 v75, v75
	v_mfma_f32_32x32x16_bf16 v[32:47], v[104:107], v[146:149], v[32:47]
	v_exp_f32_e32 v76, v76
	v_exp_f32_e32 v77, v77
	s_waitcnt lgkmcnt(1)
	v_mfma_f32_32x32x16_bf16 v[16:31], v[108:111], v[146:149], v[16:31]
	s_add_i32 m0, s22, 0x8000
	s_addk_i32 m0, 0x400
	s_add_u32 s100, s100, 0x58000
	s_addc_u32 s101, s101, 0
	global_load_lds_dwordx4 v201, s[100:101]
	v_exp_f32_e32 v78, v78
	v_exp_f32_e32 v79, v79
	v_mfma_f32_32x32x16_bf16 v[0:15], v[112:115], v[146:149], v[0:15]
	s_waitcnt vmcnt(4) lgkmcnt(0)
	s_barrier
	s_cmp_ge_u32 s24, s4
	s_mov_b32 s33, s24
	s_cbranch_scc1 .Lattn_done
	s_add_i32 s24, s33, 2
	v_mfma_f32_32x32x16_bf16 v[112:127], v[100:103], v[130:133], 0
	v_add_f32_e32 v100, v82, v80
	v_add_f32_e32 v101, v83, v81
	v_cvt_pk_bf16_f32 v158, v80, v81
	v_cvt_pk_bf16_f32 v159, v82, v83
	v_add_f32_e32 v80, v84, v100
	v_add_f32_e32 v81, v85, v101
	v_add_f32_e32 v146, v86, v80
	v_cvt_pk_bf16_f32 v160, v84, v85
	v_mfma_f32_32x32x16_bf16 v[96:111], v[96:99], v[130:133], 0
	v_add_f32_e32 v84, v87, v81
	v_cvt_pk_bf16_f32 v161, v86, v87
	ds_read_b64_tr_b16 v[80:81], v207 offset:16384
	ds_read_b64_tr_b16 v[82:83], v207 offset:16896
	v_add_f32_e32 v85, v88, v146
	v_add_f32_e32 v84, v89, v84
	v_mfma_f32_32x32x16_bf16 v[112:127], v[182:185], v[134:137], v[112:127]
	v_add_f32_e32 v146, v90, v85
	v_add_f32_e32 v147, v91, v84
	v_cvt_pk_bf16_f32 v154, v88, v89
	v_cvt_pk_bf16_f32 v155, v90, v91
	ds_read_b64_tr_b16 v[84:85], v207 offset:20480
	ds_read_b64_tr_b16 v[86:87], v207 offset:20992
	v_add_f32_e32 v88, v92, v146
	v_add_f32_e32 v89, v93, v147
	v_mfma_f32_32x32x16_bf16 v[96:111], v[178:181], v[134:137], v[96:111]
	v_add_f32_e32 v146, v94, v88
	v_add_f32_e32 v147, v95, v89
	v_cvt_pk_bf16_f32 v156, v92, v93
	v_cvt_pk_bf16_f32 v157, v94, v95
	ds_read_b64_tr_b16 v[88:89], v207 offset:24576
	ds_read_b64_tr_b16 v[90:91], v207 offset:25088
	v_add_f32_e32 v92, v64, v146
	v_add_f32_e32 v93, v65, v147
	v_mfma_f32_32x32x16_bf16 v[112:127], v[174:177], v[138:141], v[112:127]
	v_add_f32_e32 v92, v66, v92
	v_add_f32_e32 v93, v67, v93
	v_cvt_pk_bf16_f32 v150, v64, v65
	v_cvt_pk_bf16_f32 v151, v66, v67
	ds_read_b64_tr_b16 v[64:65], v207 offset:28672
	ds_read_b64_tr_b16 v[66:67], v207 offset:29184
	v_add_f32_e32 v92, v68, v92
	v_add_f32_e32 v93, v69, v93
	v_mfma_f32_32x32x16_bf16 v[96:111], v[170:173], v[138:141], v[96:111]
	v_add_f32_e32 v92, v70, v92
	v_add_f32_e32 v93, v71, v93
	v_cvt_pk_bf16_f32 v152, v68, v69
	v_cvt_pk_bf16_f32 v153, v70, v71
	v_add_f32_e32 v68, v72, v92
	v_add_f32_e32 v69, v73, v93
	v_mfma_f32_32x32x16_bf16 v[112:127], v[166:169], v[142:145], v[112:127]
	v_add_f32_e32 v68, v74, v68
	v_add_f32_e32 v69, v75, v69
	v_cvt_pk_bf16_f32 v146, v72, v73
	v_cvt_pk_bf16_f32 v147, v74, v75
	v_add_f32_e32 v68, v76, v68
	v_add_f32_e32 v69, v77, v69
	v_mfma_f32_32x32x16_bf16 v[96:111], v[162:165], v[142:145], v[96:111]
	v_add_f32_e32 v68, v78, v68
	v_add_f32_e32 v69, v79, v69
	v_cvt_pk_bf16_f32 v148, v76, v77
	v_cvt_pk_bf16_f32 v149, v78, v79
	s_nop 0
	v_exp_f32_e32 v112, v112
	v_exp_f32_e32 v113, v113
	s_waitcnt lgkmcnt(4)
	v_mfma_f32_32x32x16_bf16 v[48:63], v[80:83], v[158:161], v[48:63]
	v_add_f32_e32 v92, v68, v69
	ds_read_b64_tr_b16 v[68:69], v207 offset:17408
	ds_read_b64_tr_b16 v[70:71], v207 offset:17920
	v_exp_f32_e32 v114, v114
	v_exp_f32_e32 v115, v115
	v_mfma_f32_32x32x16_bf16 v[32:47], v[84:87], v[158:161], v[32:47]
	ds_read_b64_tr_b16 v[72:73], v207 offset:21504
	ds_read_b64_tr_b16 v[74:75], v207 offset:22016
	v_exp_f32_e32 v116, v116
	v_exp_f32_e32 v117, v117
	s_waitcnt lgkmcnt(4)
	v_mfma_f32_32x32x16_bf16 v[16:31], v[88:91], v[158:161], v[16:31]
	s_add_i32 s90, s33, 4
	s_min_u32 s90, s90, s19
	s_mul_i32 s90, s90, 0x160000
	s_add_i32 m0, s5, 0x8000
	s_add_u32 s100, s44, s90
	s_addc_u32 s101, s45, 0
	global_load_lds_dwordx4 v199, s[100:101]
	ds_read_b64_tr_b16 v[76:77], v207 offset:25600
	ds_read_b64_tr_b16 v[78:79], v207 offset:26112
	v_exp_f32_e32 v118, v118
	v_exp_f32_e32 v119, v119
	v_mfma_f32_32x32x16_bf16 v[0:15], v[64:67], v[158:161], v[0:15]
	ds_read_b64_tr_b16 v[80:81], v207 offset:29696
	ds_read_b64_tr_b16 v[82:83], v207 offset:30208
	v_exp_f32_e32 v120, v120
	v_exp_f32_e32 v121, v121
	s_waitcnt lgkmcnt(4)
	v_mfma_f32_32x32x16_bf16 v[48:63], v[68:71], v[154:157], v[48:63]
	ds_read_b64_tr_b16 v[84:85], v207 offset:18432
	ds_read_b64_tr_b16 v[86:87], v207 offset:18944
	ds_read_b128 v[68:71], v204
	v_exp_f32_e32 v122, v122
	v_exp_f32_e32 v123, v123
	v_mfma_f32_32x32x16_bf16 v[32:47], v[72:75], v[154:157], v[32:47]
	ds_read_b64_tr_b16 v[72:73], v207 offset:22528
	ds_read_b64_tr_b16 v[74:75], v207 offset:23040
	ds_read_b128 v[64:67], v204 offset:4096
	v_exp_f32_e32 v124, v124
	v_exp_f32_e32 v125, v125
	s_waitcnt lgkmcnt(6)
	v_mfma_f32_32x32x16_bf16 v[16:31], v[76:79], v[154:157], v[16:31]
	s_add_i32 m0, s32, 0x8000
	s_nop 0
	global_load_lds_dwordx4 v199, s[100:101] offset:128
	ds_read_b64_tr_b16 v[76:77], v207 offset:26624
	ds_read_b64_tr_b16 v[78:79], v207 offset:27136
	ds_read_b128 v[182:185], v128
	v_exp_f32_e32 v126, v126
	v_exp_f32_e32 v127, v127
	v_mfma_f32_32x32x16_bf16 v[0:15], v[80:83], v[154:157], v[0:15]
	ds_read_b64_tr_b16 v[80:81], v207 offset:30720
	ds_read_b64_tr_b16 v[82:83], v207 offset:31232
	ds_read_b128 v[178:181], v128 offset:4096
	v_exp_f32_e32 v96, v96
	v_exp_f32_e32 v97, v97
	s_waitcnt lgkmcnt(7)
	v_mfma_f32_32x32x16_bf16 v[48:63], v[84:87], v[150:153], v[48:63]
	ds_read_b64_tr_b16 v[84:85], v207 offset:19456
	ds_read_b64_tr_b16 v[86:87], v207 offset:19968
	ds_read_b128 v[174:177], v205
	v_exp_f32_e32 v98, v98
	v_exp_f32_e32 v99, v99
	v_mfma_f32_32x32x16_bf16 v[32:47], v[72:75], v[150:153], v[32:47]
	ds_read_b64_tr_b16 v[72:73], v207 offset:23552
	ds_read_b64_tr_b16 v[74:75], v207 offset:24064
	ds_read_b128 v[170:173], v205 offset:4096
	v_exp_f32_e32 v100, v100
	v_exp_f32_e32 v101, v101
	s_waitcnt lgkmcnt(7)
	v_mfma_f32_32x32x16_bf16 v[16:31], v[76:79], v[150:153], v[16:31]
	s_min_u32 s90, s24, s19
	s_mul_i32 s90, s90, 0x160000
	s_add_i32 m0, s22, 0x0
	s_add_u32 s100, s44, s90
	s_addc_u32 s101, s45, 0
	global_load_lds_dwordx4 v201, s[100:101]
	ds_read_b64_tr_b16 v[76:77], v207 offset:27648
	ds_read_b64_tr_b16 v[78:79], v207 offset:28160
	ds_read_b128 v[166:169], v206
	v_exp_f32_e32 v102, v102
	v_exp_f32_e32 v103, v103
	v_mfma_f32_32x32x16_bf16 v[0:15], v[80:83], v[150:153], v[0:15]
	ds_read_b64_tr_b16 v[80:81], v207 offset:31744
	ds_read_b64_tr_b16 v[82:83], v207 offset:32256
	ds_read_b128 v[162:165], v206 offset:4096
	v_exp_f32_e32 v104, v104
	v_exp_f32_e32 v105, v105
	s_waitcnt lgkmcnt(7)
	v_mfma_f32_32x32x16_bf16 v[48:63], v[84:87], v[146:149], v[48:63]
	v_exp_f32_e32 v106, v106
	v_exp_f32_e32 v107, v107
	v_mfma_f32_32x32x16_bf16 v[32:47], v[72:75], v[146:149], v[32:47]
	v_exp_f32_e32 v108, v108
	v_exp_f32_e32 v109, v109
	s_waitcnt lgkmcnt(1)
	v_mfma_f32_32x32x16_bf16 v[16:31], v[76:79], v[146:149], v[16:31]
	s_add_i32 m0, s22, 0x0
	s_addk_i32 m0, 0x400
	s_add_u32 s100, s100, 0x58000
	s_addc_u32 s101, s101, 0
	global_load_lds_dwordx4 v201, s[100:101]
	v_exp_f32_e32 v110, v110
	v_exp_f32_e32 v111, v111
	v_mfma_f32_32x32x16_bf16 v[0:15], v[80:83], v[146:149], v[0:15]
	s_waitcnt vmcnt(4) lgkmcnt(0)
	s_barrier
	v_add_f32_e32 v186, v209, v92
	v_mfma_f32_32x32x16_bf16 v[80:95], v[68:71], v[130:133], 0
	v_add_f32_e32 v68, v114, v112
	v_add_f32_e32 v69, v115, v113
	v_cvt_pk_bf16_f32 v158, v112, v113
	v_cvt_pk_bf16_f32 v159, v114, v115
	v_add_f32_e32 v68, v116, v68
	v_add_f32_e32 v112, v117, v69
	v_add_f32_e32 v146, v118, v68
	v_cvt_pk_bf16_f32 v160, v116, v117
	v_mfma_f32_32x32x16_bf16 v[64:79], v[64:67], v[130:133], 0
	v_add_f32_e32 v116, v119, v112
	v_cvt_pk_bf16_f32 v161, v118, v119
	ds_read_b64_tr_b16 v[112:113], v207 offset:32768
	ds_read_b64_tr_b16 v[114:115], v207 offset:33280
	v_add_f32_e32 v117, v120, v146
	v_add_f32_e32 v116, v121, v116
	v_mfma_f32_32x32x16_bf16 v[80:95], v[182:185], v[134:137], v[80:95]
	v_add_f32_e32 v146, v122, v117
	v_add_f32_e32 v147, v123, v116
	v_cvt_pk_bf16_f32 v154, v120, v121
	v_cvt_pk_bf16_f32 v155, v122, v123
	ds_read_b64_tr_b16 v[116:117], v207 offset:36864
	ds_read_b64_tr_b16 v[118:119], v207 offset:37376
	v_add_f32_e32 v120, v124, v146
	v_add_f32_e32 v121, v125, v147
	v_mfma_f32_32x32x16_bf16 v[64:79], v[178:181], v[134:137], v[64:79]
	v_add_f32_e32 v146, v126, v120
	v_add_f32_e32 v147, v127, v121
	v_cvt_pk_bf16_f32 v156, v124, v125
	v_cvt_pk_bf16_f32 v157, v126, v127
	ds_read_b64_tr_b16 v[120:121], v207 offset:40960
	ds_read_b64_tr_b16 v[122:123], v207 offset:41472
	v_add_f32_e32 v124, v96, v146
	v_add_f32_e32 v125, v97, v147
	v_mfma_f32_32x32x16_bf16 v[80:95], v[174:177], v[138:141], v[80:95]
	v_add_f32_e32 v124, v98, v124
	v_add_f32_e32 v125, v99, v125
	v_cvt_pk_bf16_f32 v150, v96, v97
	v_cvt_pk_bf16_f32 v151, v98, v99
	ds_read_b64_tr_b16 v[96:97], v207 offset:45056
	ds_read_b64_tr_b16 v[98:99], v207 offset:45568
	v_add_f32_e32 v124, v100, v124
	v_add_f32_e32 v125, v101, v125
	v_mfma_f32_32x32x16_bf16 v[64:79], v[170:173], v[138:141], v[64:79]
	v_add_f32_e32 v124, v102, v124
	v_add_f32_e32 v125, v103, v125
	v_cvt_pk_bf16_f32 v152, v100, v101
	v_cvt_pk_bf16_f32 v153, v102, v103
	v_add_f32_e32 v100, v104, v124
	v_add_f32_e32 v101, v105, v125
	v_mfma_f32_32x32x16_bf16 v[80:95], v[166:169], v[142:145], v[80:95]
	v_add_f32_e32 v100, v106, v100
	v_add_f32_e32 v101, v107, v101
	v_cvt_pk_bf16_f32 v146, v104, v105
	v_cvt_pk_bf16_f32 v147, v106, v107
	v_add_f32_e32 v100, v108, v100
	v_add_f32_e32 v101, v109, v101
	v_mfma_f32_32x32x16_bf16 v[64:79], v[162:165], v[142:145], v[64:79]
	v_add_f32_e32 v100, v110, v100
	v_add_f32_e32 v101, v111, v101
	v_cvt_pk_bf16_f32 v148, v108, v109
	v_cvt_pk_bf16_f32 v149, v110, v111
	v_add_f32_e32 v100, v100, v101
	v_exp_f32_e32 v80, v80
	v_exp_f32_e32 v81, v81
	s_waitcnt lgkmcnt(4)
	v_mfma_f32_32x32x16_bf16 v[48:63], v[112:115], v[158:161], v[48:63]
	v_add_f32_e32 v209, v186, v100
	ds_read_b64_tr_b16 v[100:101], v207 offset:33792
	ds_read_b64_tr_b16 v[102:103], v207 offset:34304
	v_exp_f32_e32 v82, v82
	v_exp_f32_e32 v83, v83
	v_mfma_f32_32x32x16_bf16 v[32:47], v[116:119], v[158:161], v[32:47]
	ds_read_b64_tr_b16 v[104:105], v207 offset:37888
	ds_read_b64_tr_b16 v[106:107], v207 offset:38400
	v_exp_f32_e32 v84, v84
	v_exp_f32_e32 v85, v85
	s_waitcnt lgkmcnt(4)
	v_mfma_f32_32x32x16_bf16 v[16:31], v[120:123], v[158:161], v[16:31]
	s_add_i32 s90, s33, 5
	s_min_u32 s90, s90, s19
	s_mul_i32 s90, s90, 0x160000
	s_add_i32 m0, s5, 0x0
	s_add_u32 s100, s44, s90
	s_addc_u32 s101, s45, 0
	global_load_lds_dwordx4 v199, s[100:101]
	ds_read_b64_tr_b16 v[108:109], v207 offset:41984
	ds_read_b64_tr_b16 v[110:111], v207 offset:42496
	v_exp_f32_e32 v86, v86
	v_exp_f32_e32 v87, v87
	v_mfma_f32_32x32x16_bf16 v[0:15], v[96:99], v[158:161], v[0:15]
	ds_read_b64_tr_b16 v[112:113], v207 offset:46080
	ds_read_b64_tr_b16 v[114:115], v207 offset:46592
	v_exp_f32_e32 v88, v88
	v_exp_f32_e32 v89, v89
	s_waitcnt lgkmcnt(4)
	v_mfma_f32_32x32x16_bf16 v[48:63], v[100:103], v[154:157], v[48:63]
	ds_read_b64_tr_b16 v[116:117], v207 offset:34816
	ds_read_b64_tr_b16 v[118:119], v207 offset:35328
	ds_read_b128 v[100:103], v204 offset:16384
	v_exp_f32_e32 v90, v90
	v_exp_f32_e32 v91, v91
	v_mfma_f32_32x32x16_bf16 v[32:47], v[104:107], v[154:157], v[32:47]
	ds_read_b64_tr_b16 v[104:105], v207 offset:38912
	ds_read_b64_tr_b16 v[106:107], v207 offset:39424
	ds_read_b128 v[96:99], v204 offset:20480
	v_exp_f32_e32 v92, v92
	v_exp_f32_e32 v93, v93
	s_waitcnt lgkmcnt(6)
	v_mfma_f32_32x32x16_bf16 v[16:31], v[108:111], v[154:157], v[16:31]
	s_add_i32 m0, s32, 0x0
	s_nop 0
	global_load_lds_dwordx4 v199, s[100:101] offset:128
	ds_read_b64_tr_b16 v[108:109], v207 offset:43008
	ds_read_b64_tr_b16 v[110:111], v207 offset:43520
	ds_read_b128 v[182:185], v128 offset:16384
	v_exp_f32_e32 v94, v94
	v_exp_f32_e32 v95, v95
	v_mfma_f32_32x32x16_bf16 v[0:15], v[112:115], v[154:157], v[0:15]
	ds_read_b64_tr_b16 v[112:113], v207 offset:47104
	ds_read_b64_tr_b16 v[114:115], v207 offset:47616
	ds_read_b128 v[178:181], v128 offset:20480
	v_exp_f32_e32 v64, v64
	v_exp_f32_e32 v65, v65
	s_waitcnt lgkmcnt(7)
	v_mfma_f32_32x32x16_bf16 v[48:63], v[116:119], v[150:153], v[48:63]
	ds_read_b64_tr_b16 v[116:117], v207 offset:35840
	ds_read_b64_tr_b16 v[118:119], v207 offset:36352
	ds_read_b128 v[174:177], v205 offset:16384
	v_exp_f32_e32 v66, v66
	v_exp_f32_e32 v67, v67
	v_mfma_f32_32x32x16_bf16 v[32:47], v[104:107], v[150:153], v[32:47]
	ds_read_b64_tr_b16 v[104:105], v207 offset:39936
	ds_read_b64_tr_b16 v[106:107], v207 offset:40448
	ds_read_b128 v[170:173], v205 offset:20480
	v_exp_f32_e32 v68, v68
	v_exp_f32_e32 v69, v69
	s_waitcnt lgkmcnt(7)
	v_mfma_f32_32x32x16_bf16 v[16:31], v[108:111], v[150:153], v[16:31]
	s_add_i32 s90, s33, 3
	s_min_u32 s90, s90, s19
	s_mul_i32 s90, s90, 0x160000
	s_add_i32 m0, s22, 0x4000
	s_add_u32 s100, s44, s90
	s_addc_u32 s101, s45, 0
	global_load_lds_dwordx4 v201, s[100:101]
	ds_read_b64_tr_b16 v[108:109], v207 offset:44032
	ds_read_b64_tr_b16 v[110:111], v207 offset:44544
	ds_read_b128 v[166:169], v206 offset:16384
	v_exp_f32_e32 v70, v70
	v_exp_f32_e32 v71, v71
	v_mfma_f32_32x32x16_bf16 v[0:15], v[112:115], v[150:153], v[0:15]
	ds_read_b64_tr_b16 v[112:113], v207 offset:48128
	ds_read_b64_tr_b16 v[114:115], v207 offset:48640
	ds_read_b128 v[162:165], v206 offset:20480
	v_exp_f32_e32 v72, v72
	v_exp_f32_e32 v73, v73
	s_waitcnt lgkmcnt(7)
	v_mfma_f32_32x32x16_bf16 v[48:63], v[116:119], v[146:149], v[48:63]
	v_exp_f32_e32 v74, v74
	v_exp_f32_e32 v75, v75
	v_mfma_f32_32x32x16_bf16 v[32:47], v[104:107], v[146:149], v[32:47]
	v_exp_f32_e32 v76, v76
	v_exp_f32_e32 v77, v77
	s_waitcnt lgkmcnt(1)
	v_mfma_f32_32x32x16_bf16 v[16:31], v[108:111], v[146:149], v[16:31]
	s_add_i32 m0, s22, 0x4000
	s_addk_i32 m0, 0x400
	s_add_u32 s100, s100, 0x58000
	s_addc_u32 s101, s101, 0
	global_load_lds_dwordx4 v201, s[100:101]
	v_exp_f32_e32 v78, v78
	v_exp_f32_e32 v79, v79
	v_mfma_f32_32x32x16_bf16 v[0:15], v[112:115], v[146:149], v[0:15]
	s_waitcnt vmcnt(4) lgkmcnt(0)
	s_barrier
	s_cmp_ge_u32 s24, s4
	s_mov_b32 s33, s24
	s_cbranch_scc0 .LBB0_86
.Lattn_done:
	ds_bpermute_b32 v64, v246, v209
	s_waitcnt vmcnt(0)
	s_barrier
	s_cmpk_lt_u32 s17, 0x100
	s_mov_b64 s[10:11], -1
	s_waitcnt lgkmcnt(0)
	v_add_f32_e32 v64, v209, v64
	v_div_scale_f32 v65, s[4:5], v64, v64, 1.0
	v_rcp_f32_e32 v66, v65
	v_div_scale_f32 v67, vcc, 1.0, v64, 1.0
	s_cselect_b64 s[4:5], -1, 0
	v_fma_f32 v68, -v65, v66, 1.0
	v_fmac_f32_e32 v66, v68, v66
	v_mul_f32_e32 v68, v67, v66
	v_fma_f32 v69, -v65, v68, v67
	v_fmac_f32_e32 v68, v69, v66
	v_fma_f32 v65, -v65, v68, v67
	v_div_fmas_f32 v65, v65, v66, v68
	v_div_fixup_f32 v134, v65, v64, 1.0
	s_and_b64 vcc, exec, s[4:5]
	s_cbranch_vccnz .LBB0_89
	s_lshl_b32 s10, s18, 14
	s_add_i32 s10, s10, 0
	v_mul_f32_e32 v64, v48, v134
	v_lshl_add_u32 v65, v202, 2, s10
	v_mul_f32_e32 v66, v49, v134
	ds_write2st64_b32 v65, v64, v66 offset1:1
	v_mul_f32_e32 v64, v50, v134
	v_mul_f32_e32 v66, v51, v134
	ds_write2st64_b32 v65, v64, v66 offset0:2 offset1:3
	v_mul_f32_e32 v64, v52, v134
	v_mul_f32_e32 v66, v53, v134
	ds_write2st64_b32 v65, v64, v66 offset0:4 offset1:5
	v_mul_f32_e32 v64, v54, v134
	v_mul_f32_e32 v66, v55, v134
	ds_write2st64_b32 v65, v64, v66 offset0:6 offset1:7
	v_mul_f32_e32 v64, v56, v134
	v_mul_f32_e32 v66, v57, v134
	ds_write2st64_b32 v65, v64, v66 offset0:8 offset1:9
	v_mul_f32_e32 v64, v58, v134
	v_mul_f32_e32 v66, v59, v134
	ds_write2st64_b32 v65, v64, v66 offset0:10 offset1:11
	v_mul_f32_e32 v64, v60, v134
	v_mul_f32_e32 v66, v61, v134
	ds_write2st64_b32 v65, v64, v66 offset0:12 offset1:13
	v_mul_f32_e32 v64, v62, v134
	v_mul_f32_e32 v66, v63, v134
	ds_write2st64_b32 v65, v64, v66 offset0:14 offset1:15
	v_mul_f32_e32 v64, v32, v134
	v_mul_f32_e32 v66, v33, v134
	ds_write2st64_b32 v65, v64, v66 offset0:16 offset1:17
	v_mul_f32_e32 v64, v34, v134
	v_mul_f32_e32 v66, v35, v134
	ds_write2st64_b32 v65, v64, v66 offset0:18 offset1:19
	v_mul_f32_e32 v64, v36, v134
	v_mul_f32_e32 v66, v37, v134
	ds_write2st64_b32 v65, v64, v66 offset0:20 offset1:21
	v_mul_f32_e32 v64, v38, v134
	v_mul_f32_e32 v66, v39, v134
	ds_write2st64_b32 v65, v64, v66 offset0:22 offset1:23
	v_mul_f32_e32 v64, v40, v134
	v_mul_f32_e32 v66, v41, v134
	ds_write2st64_b32 v65, v64, v66 offset0:24 offset1:25
	v_mul_f32_e32 v64, v42, v134
	v_mul_f32_e32 v66, v43, v134
	ds_write2st64_b32 v65, v64, v66 offset0:26 offset1:27
	v_mul_f32_e32 v64, v44, v134
	v_mul_f32_e32 v66, v45, v134
	ds_write2st64_b32 v65, v64, v66 offset0:28 offset1:29
	v_mul_f32_e32 v64, v46, v134
	v_mul_f32_e32 v66, v47, v134
	ds_write2st64_b32 v65, v64, v66 offset0:30 offset1:31
	v_mul_f32_e32 v64, v16, v134
	v_mul_f32_e32 v66, v17, v134
	ds_write2st64_b32 v65, v64, v66 offset0:32 offset1:33
	v_mul_f32_e32 v64, v18, v134
	v_mul_f32_e32 v66, v19, v134
	ds_write2st64_b32 v65, v64, v66 offset0:34 offset1:35
	v_mul_f32_e32 v64, v20, v134
	v_mul_f32_e32 v66, v21, v134
	ds_write2st64_b32 v65, v64, v66 offset0:36 offset1:37
	v_mul_f32_e32 v64, v22, v134
	v_mul_f32_e32 v66, v23, v134
	ds_write2st64_b32 v65, v64, v66 offset0:38 offset1:39
	v_mul_f32_e32 v64, v24, v134
	v_mul_f32_e32 v66, v25, v134
	ds_write2st64_b32 v65, v64, v66 offset0:40 offset1:41
	v_mul_f32_e32 v64, v26, v134
	v_mul_f32_e32 v66, v27, v134
	ds_write2st64_b32 v65, v64, v66 offset0:42 offset1:43
	v_mul_f32_e32 v64, v28, v134
	v_mul_f32_e32 v66, v29, v134
	ds_write2st64_b32 v65, v64, v66 offset0:44 offset1:45
	v_mul_f32_e32 v64, v30, v134
	v_mul_f32_e32 v66, v31, v134
	ds_write2st64_b32 v65, v64, v66 offset0:46 offset1:47
	v_mul_f32_e32 v64, v0, v134
	v_mul_f32_e32 v66, v1, v134
	ds_write2st64_b32 v65, v64, v66 offset0:48 offset1:49
	v_mul_f32_e32 v64, v2, v134
	v_mul_f32_e32 v66, v3, v134
	ds_write2st64_b32 v65, v64, v66 offset0:50 offset1:51
	v_mul_f32_e32 v64, v4, v134
	v_mul_f32_e32 v66, v5, v134
	ds_write2st64_b32 v65, v64, v66 offset0:52 offset1:53
	v_mul_f32_e32 v64, v6, v134
	v_mul_f32_e32 v66, v7, v134
	ds_write2st64_b32 v65, v64, v66 offset0:54 offset1:55
	v_mul_f32_e32 v64, v8, v134
	v_mul_f32_e32 v66, v9, v134
	ds_write2st64_b32 v65, v64, v66 offset0:56 offset1:57
	v_mul_f32_e32 v64, v10, v134
	v_mul_f32_e32 v66, v11, v134
	ds_write2st64_b32 v65, v64, v66 offset0:58 offset1:59
	v_mul_f32_e32 v64, v12, v134
	v_mul_f32_e32 v66, v13, v134
	ds_write2st64_b32 v65, v64, v66 offset0:60 offset1:61
	v_mul_f32_e32 v64, v14, v134
	v_mul_f32_e32 v66, v15, v134
	s_mov_b64 s[10:11], 0
	ds_write2st64_b32 v65, v64, v66 offset0:62 offset1:63
